# v11 + cross-attn K/V cache f32->bf16 conversion moved from prologue to the idle tail of phase 4 (WGs without a 6th tile)
# speedup vs baseline: 1.0085x; 1.0070x over previous
; __device__ __forceinline__ void phase_prep(const Params& p, LAS unsigned char* lds) {
;     ...
;     cvt_rows(p.in[4], (bf16_t*)(ws + O_MKB) + (size_t)4096 * D, (size_t)8192 * D / 8, gtid, gn);
;     cvt_rows(p.in[5], (bf16_t*)(ws + O_MVB) + (size_t)4096 * D, (size_t)8192 * D / 8, gtid, gn);
;     for (size_t i = gtid; i < 4 * 128 * 128 / 2; i += gn) { const int e = (int)i * 2, t = (e >> 7) & 127, s = e & 127;
;         const float a = s <= t ? p.in[19][e] : 0.f, b = (s + 1) <= t ? p.in[19][e + 1] : 0.f; ((unsigned*)(ws + O_WSB))[i] = pk2(a, b); }
.LBB0_96:
	s_or_b64 exec, exec, s[8:9]
	s_mov_b64 s[0:1], 0x100000
	v_cmp_gt_u64_e32 vcc, s[0:1], v[0:1]
	s_and_saveexec_b64 s[8:9], vcc
.LBB0_101:
	s_or_b64 exec, exec, s[8:9]
	s_mov_b64 s[0:1], 0x8000
	v_cmp_gt_u64_e32 vcc, s[0:1], v[0:1]
	s_and_saveexec_b64 s[8:9], vcc
	s_cbranch_execz .LBB0_108
	s_lshl_b64 s[0:1], s[2:3], 11
	s_add_u32 s0, s52, s0
	s_addc_u32 s1, s53, s1
	v_lshl_add_u64 v[2:3], v[208:209], 2, s[0:1]
	s_mov_b64 s[0:1], 0x3001000
	v_lshlrev_b32_e32 v4, 1, v208
	v_lshl_add_u64 v[2:3], v[2:3], 0, s[0:1]
	s_lshl_b64 s[10:11], s[58:59], 11
	v_lshl_add_u32 v4, s2, 10, v4
	s_waitcnt lgkmcnt(0)
	s_lshl_b32 s0, s82, 10
	s_mov_b64 s[12:13], 0
	v_mov_b32_e32 v5, 0
	s_mov_b64 s[14:15], 0x7fff
	s_branch .LBB0_104

; #define GASP __attribute__((address_space(1)))
; __device__ __forceinline__ void cvt_rows(const float* src, bf16_t* dst, size_t n8, size_t gtid, size_t gn) {
;     for (size_t i = gtid; i < n8; i += gn) { const f32x4 a = *(const GASP f32x4*)(src + 8 * i), b = *(const GASP f32x4*)(src + 8 * i + 4);
;         u32x4 o; o.x = pk2(a[0], a[1]); o.y = pk2(a[2], a[3]); o.z = pk2(b[0], b[1]); o.w = pk2(b[2], b[3]); *(GASP u32x4*)(dst + 8 * i) = o; }
; __device__ __forceinline__ void phase_prep(const Params& p, LAS unsigned char* lds) {
;     ...
;     cvt_rows(p.in[4], (bf16_t*)(ws + O_MKB) + (size_t)4096 * D, (size_t)8192 * D / 8, gtid, gn);
;     cvt_rows(p.in[5], (bf16_t*)(ws + O_MVB) + (size_t)4096 * D, (size_t)8192 * D / 8, gtid, gn);
.LBB0_819:
	v_readlane_b32 s0, v252, 1
	v_readlane_b32 s1, v252, 2
	s_waitcnt vmcnt(0)
	s_barrier
	s_cmp_lt_u32 s2, 40
	s_cbranch_scc1 .Lcv_done
	s_load_dwordx4 s[4:7], s[0:1], 0x20
	s_sub_u32 s8, s2, 40
	v_lshlrev_b32_e32 v0, 5, v208
	v_lshlrev_b32_e32 v2, 4, v208
	s_add_u32 s24, s52, 0x1bba1000
	s_addc_u32 s25, s53, 0
	s_add_u32 s26, s52, 0x1d3a1000
	s_addc_u32 s27, s53, 0
	s_waitcnt lgkmcnt(0)
.Lcv_loop:
	s_lshl_b32 s10, s8, 14
	s_add_u32 s14, s4, s10
	s_addc_u32 s15, s5, 0
	s_add_u32 s16, s6, s10
	s_addc_u32 s17, s7, 0
	global_load_dwordx4 v[4:7], v0, s[14:15]
	global_load_dwordx4 v[8:11], v0, s[14:15] offset:16
	global_load_dwordx4 v[12:15], v0, s[16:17]
	global_load_dwordx4 v[16:19], v0, s[16:17] offset:16
	s_add_u32 s9, s8, 216
	s_cmp_lt_u32 s9, 2048
	s_cbranch_scc0 .Lcv_waitA
	s_lshl_b32 s10, s9, 14
	s_add_u32 s14, s4, s10
	s_addc_u32 s15, s5, 0
	s_add_u32 s16, s6, s10
	s_addc_u32 s17, s7, 0
	global_load_dwordx4 v[20:23], v0, s[14:15]
	global_load_dwordx4 v[24:27], v0, s[14:15] offset:16
	global_load_dwordx4 v[28:31], v0, s[16:17]
	global_load_dwordx4 v[32:35], v0, s[16:17] offset:16
.Lcv_waitA:
	s_waitcnt vmcnt(0)
	s_lshl_b32 s12, s8, 13
	v_cvt_pk_bf16_f32 v4, v4, v5
	v_cvt_pk_bf16_f32 v5, v6, v7
	v_cvt_pk_bf16_f32 v6, v8, v9
	v_cvt_pk_bf16_f32 v7, v10, v11
	v_cvt_pk_bf16_f32 v12, v12, v13
	v_cvt_pk_bf16_f32 v13, v14, v15
	v_cvt_pk_bf16_f32 v14, v16, v17
	v_cvt_pk_bf16_f32 v15, v18, v19
	s_add_u32 s18, s24, s12
	s_addc_u32 s19, s25, 0
	s_add_u32 s20, s26, s12
	s_addc_u32 s21, s27, 0
	global_store_dwordx4 v2, v[4:7], s[18:19]
	global_store_dwordx4 v2, v[12:15], s[20:21]
	s_cmp_lt_u32 s9, 2048
	s_cbranch_scc0 .Lcv_done
	s_lshl_b32 s12, s9, 13
	v_cvt_pk_bf16_f32 v20, v20, v21
	v_cvt_pk_bf16_f32 v21, v22, v23
	v_cvt_pk_bf16_f32 v22, v24, v25
	v_cvt_pk_bf16_f32 v23, v26, v27
	v_cvt_pk_bf16_f32 v28, v28, v29
	v_cvt_pk_bf16_f32 v29, v30, v31
	v_cvt_pk_bf16_f32 v30, v32, v33
	v_cvt_pk_bf16_f32 v31, v34, v35
	s_add_u32 s18, s24, s12
	s_addc_u32 s19, s25, 0
	s_add_u32 s20, s26, s12
	s_addc_u32 s21, s27, 0
	global_store_dwordx4 v2, v[20:23], s[18:19]
	global_store_dwordx4 v2, v[28:31], s[20:21]
	s_add_u32 s8, s8, 432
	s_cmp_lt_u32 s8, 2048
	s_cbranch_scc1 .Lcv_loop
.Lcv_done:
	s_load_dwordx2 s[82:83], s[0:1], 0x128
